# P5: wave owns 64 contiguous cols (B-fragment remap) + lane-pair exchange -> full-line stores; P6 same exchange
# speedup vs baseline: 1.0196x; 1.0064x over previous
.LBB0_437:
	s_lshl_b32 s12, s12, 5
	s_and_b32 s18, s12, 0x60
	s_add_i32 s51, s43, 0x18000
	s_mov_b64 s[12:13], 0x80
	v_lshl_add_u64 v[6:7], v[6:7], 0, s[12:13]
	s_mov_b32 m0, s51
	s_add_i32 s52, s43, 0x1a000
	s_lshl_b32 s15, s7, 13
	s_lshl_b32 s19, s18, 8
	s_waitcnt vmcnt(2)
	s_barrier
	global_load_lds_dwordx4 v[6:7], off
	v_lshl_add_u64 v[4:5], v[4:5], 0, s[12:13]
	s_mov_b32 m0, s52
	s_add_i32 s53, s43, 0x8000
	s_add_i32 s54, s43, 0xa000
	global_load_lds_dwordx4 v[4:5], off
	v_lshl_add_u64 v[0:1], v[0:1], 0, s[12:13]
	s_mov_b32 m0, s53
	s_add_u32 s16, s38, 0x80080
	global_load_lds_dwordx4 v[0:1], off
	v_lshl_add_u64 v[0:1], v[2:3], 0, s[12:13]
	s_mov_b32 m0, s54
	s_addc_u32 s17, s39, 0
	s_add_i32 s55, s43, 0x1c000
	global_load_lds_dwordx4 v[0:1], off
	v_lshl_add_u64 v[0:1], s[16:17], 0, v[130:131]
	s_mov_b32 m0, s55
	s_add_i32 s56, s43, 0x1e000
	global_load_lds_dwordx4 v[0:1], off
	v_lshl_add_u64 v[0:1], s[16:17], 0, v[134:135]
	s_mov_b32 m0, s56
	s_sext_i32_i8 s29, s6
	global_load_lds_dwordx4 v[0:1], off
	v_and_b32_e32 v0, 15, v168
	v_lshl_or_b32 v144, s7, 6, v0
	v_lshlrev_b32_e32 v1, 1, v11
	v_lshlrev_b32_e32 v2, 2, v144
	v_lshl_or_b32 v0, v0, 6, v1
	v_and_b32_e32 v3, 32, v2
	v_bitop3_b32 v145, v0, s15, v3 bitop3:0xde
	v_lshlrev_b32_e32 v0, 6, v168
	s_movk_i32 s6, 0x3c0
	v_and_or_b32 v0, v0, s6, v1
	v_lshlrev_b32_e32 v1, 2, v168
	v_and_b32_e32 v1, 32, v1
	v_bitop3_b32 v0, s19, v0, v1 bitop3:0xf6
	v_lshlrev_b32_e32 v1, 9, v168
	v_add_u32_e32 v154, 0x20000, v2
	v_and_b32_e32 v1, 0x70000, v1
	v_lshlrev_b32_e32 v2, 12, v10
	v_or3_b32 v1, v8, v1, v2
	v_add_u32_e32 v136, v1, v9
	v_lshlrev_b32_e32 v1, 5, v12
	s_waitcnt vmcnt(6)
	v_and_b32_e32 v1, 0xf0000, v1
	s_cmpk_lt_u32 s14, 0x100
	v_or3_b32 v1, v8, v1, v2
	s_cselect_b64 s[14:15], -1, 0
	v_and_b32_e32 v172, 1, v144
	v_and_b32_e32 v144, -2, v144
	v_or_b32_e32 v146, 16, v144
	v_or_b32_e32 v147, 32, v144
	v_or_b32_e32 v148, 48, v144
	v_add_u32_e32 v149, 0x80, v144
	v_add_u32_e32 v150, 0x90, v144
	v_add_u32_e32 v151, 0xa0, v144
	v_add_u32_e32 v152, 0xb0, v144
	s_lshl_b32 s19, s18, 1
	v_or_b32_e32 v153, s19, v11
	v_lshl_or_b32 v153, v172, 5, v153
	v_mov_b32_e32 v137, v131
	v_add_u32_e32 v138, v1, v9
	v_mov_b32_e32 v139, v131
	s_mov_b32 s61, 0
	v_mov_b64_e32 v[140:141], 0x800
	v_mov_b64_e32 v[142:143], 0x7ff
	v_or_b32_e32 v155, 0x10000, v0
	v_add_u32_e32 v156, 0x10400, v0
	v_add_u32_e32 v157, 0x10800, v0
	v_add_u32_e32 v158, 0x10c00, v0
	v_or_b32_e32 v159, 0x11000, v0
	v_add_u32_e32 v160, 0x11400, v0
	v_add_u32_e32 v161, 0x11800, v0
	v_add_u32_e32 v162, 0x11c00, v0
	s_add_i32 s57, s43, 0xc000
	s_add_i32 s58, s43, 0xe000
	v_or_b32_e32 v163, 0x18000, v0
	v_add_u32_e32 v164, 0x18400, v0
	v_add_u32_e32 v165, 0x18800, v0
	v_add_u32_e32 v166, 0x18c00, v0
	v_or_b32_e32 v167, 0x19000, v0
	v_add_u32_e32 v169, 0x19400, v0
	v_add_u32_e32 v170, 0x19800, v0
	v_add_u32_e32 v171, 0x19c00, v0
	s_mov_b32 s59, 0
	s_barrier
	s_branch .LBB0_440

.LBB0_450:
	s_mov_b32 s100, 0x4000
	s_mov_b32 s101, 0
	s_mov_b32 vcc_lo, 0x55555555
	s_mov_b32 vcc_hi, 0x55555555
	v_lshl_add_u32 v172, s61, 10, v154
	ds_read2_b32 v[176:177], v172 offset1:16
	s_lshl_b32 s17, s28, 8
	s_ashr_i32 s28, s28, 3
	v_lshl_or_b32 v174, s29, 8, v153
	s_ashr_i32 s29, s28, 31
	v_add_u32_e32 v178, s17, v144
	s_waitcnt lgkmcnt(0)
	v_pk_mul_f32 v[126:127], v[126:127], v[176:177] op_sel_hi:[1,0]
	v_pk_mul_f32 v[124:125], v[124:125], v[176:177] op_sel_hi:[1,0]
	v_pk_mul_f32 v[120:121], v[120:121], v[176:177] op_sel_hi:[1,0]
	s_lshl_b64 s[28:29], s[28:29], 23
	v_ashrrev_i32_e32 v179, 31, v178
	v_pk_mul_f32 v[122:123], v[122:123], v[176:177] op_sel_hi:[1,0]
	v_max_f32_e32 v124, 0, v124
	v_max_f32_e32 v120, 0, v120
	v_max_f32_e32 v125, 0, v125
	v_max_f32_e32 v121, 0, v121
	v_max_f32_e32 v126, 0, v126
	v_max_f32_e32 v127, 0, v127
	s_add_u32 s28, s22, s28
	v_ashrrev_i32_e32 v175, 31, v174
	v_lshlrev_b64 v[178:179], 14, v[178:179]
	v_pk_mul_f32 v[124:125], v[124:125], v[124:125]
	v_pk_mul_f32 v[120:121], v[120:121], v[120:121]
	v_max_f32_e32 v122, 0, v122
	v_max_f32_e32 v123, 0, v123
	v_pk_mul_f32 v[126:127], v[126:127], v[126:127]
	s_addc_u32 s29, s23, s29
	v_pk_mul_f32 v[180:181], v[122:123], v[122:123]
	v_cvt_pk_bf16_f32 v184, v124, v125
	v_cvt_pk_bf16_f32 v185, v126, v127
	v_cvt_pk_bf16_f32 v186, v120, v121
	v_lshl_add_u64 v[126:127], s[28:29], 0, v[178:179]
	v_lshlrev_b64 v[120:121], 1, v[174:175]
	v_pk_mul_f32 v[112:113], v[112:113], v[176:177] op_sel_hi:[1,0]
	v_cvt_pk_bf16_f32 v187, v180, v181
	v_lshl_add_u64 v[126:127], v[126:127], 0, v[120:121]
	v_pk_mul_f32 v[118:119], v[118:119], v[176:177] op_sel_hi:[1,0]
	v_pk_mul_f32 v[116:117], v[116:117], v[176:177] op_sel_hi:[1,0]
	v_pk_mul_f32 v[114:115], v[114:115], v[176:177] op_sel_hi:[1,0]
	v_max_f32_e32 v112, 0, v112
	v_max_f32_e32 v113, 0, v113
	v_max_f32_e32 v116, 0, v116
	v_max_f32_e32 v117, 0, v117
	v_pk_mul_f32 v[122:123], v[112:113], v[112:113]
	v_max_f32_e32 v112, 0, v118
	v_max_f32_e32 v114, 0, v114
	v_max_f32_e32 v113, 0, v119
	v_max_f32_e32 v115, 0, v115
	v_pk_mul_f32 v[116:117], v[116:117], v[116:117]
	v_pk_mul_f32 v[118:119], v[112:113], v[112:113]
	v_pk_mul_f32 v[124:125], v[114:115], v[114:115]
	v_cvt_pk_bf16_f32 v112, v116, v117
	v_cvt_pk_bf16_f32 v113, v118, v119
	v_cvt_pk_bf16_f32 v114, v122, v123
	v_cvt_pk_bf16_f32 v115, v124, v125
	s_nop 1
	v_cndmask_b32_dpp v200, v112, v184, vcc quad_perm:[0,0,2,2] row_mask:0xf bank_mask:0xf
	v_cndmask_b32_dpp v201, v113, v185, vcc quad_perm:[0,0,2,2] row_mask:0xf bank_mask:0xf
	v_cndmask_b32_dpp v202, v114, v186, vcc quad_perm:[0,0,2,2] row_mask:0xf bank_mask:0xf
	v_cndmask_b32_dpp v203, v115, v187, vcc quad_perm:[0,0,2,2] row_mask:0xf bank_mask:0xf
	s_not_b64 vcc, vcc
	v_cndmask_b32_dpp v112, v184, v112, vcc quad_perm:[1,1,3,3] row_mask:0xf bank_mask:0xf
	v_cndmask_b32_dpp v113, v185, v113, vcc quad_perm:[1,1,3,3] row_mask:0xf bank_mask:0xf
	v_cndmask_b32_dpp v114, v186, v114, vcc quad_perm:[1,1,3,3] row_mask:0xf bank_mask:0xf
	v_cndmask_b32_dpp v115, v187, v115, vcc quad_perm:[1,1,3,3] row_mask:0xf bank_mask:0xf
	s_not_b64 vcc, vcc
	v_lshl_add_u64 v[216:217], v[126:127], 0, s[100:101]
	global_store_dwordx4 v[126:127], v[200:203], off nt
	global_store_dwordx4 v[216:217], v[112:115], off nt
	s_nop 1
	v_mov_b32_e32 v114, v177
	v_add_u32_e32 v112, s17, v146
	v_pk_mul_f32 v[108:109], v[108:109], v[114:115] op_sel_hi:[1,0]
	v_pk_mul_f32 v[104:105], v[104:105], v[114:115] op_sel_hi:[1,0]
	v_ashrrev_i32_e32 v113, 31, v112
	v_pk_mul_f32 v[110:111], v[110:111], v[114:115] op_sel_hi:[1,0]
	v_pk_mul_f32 v[106:107], v[106:107], v[114:115] op_sel_hi:[1,0]
	v_max_f32_e32 v108, 0, v108
	v_max_f32_e32 v104, 0, v104
	v_max_f32_e32 v109, 0, v109
	v_max_f32_e32 v105, 0, v105
	v_lshlrev_b64 v[112:113], 14, v[112:113]
	v_pk_mul_f32 v[108:109], v[108:109], v[108:109]
	v_pk_mul_f32 v[116:117], v[104:105], v[104:105]
	v_max_f32_e32 v104, 0, v110
	v_max_f32_e32 v106, 0, v106
	v_max_f32_e32 v105, 0, v111
	v_max_f32_e32 v107, 0, v107
	v_pk_mul_f32 v[110:111], v[104:105], v[104:105]
	v_pk_mul_f32 v[118:119], v[106:107], v[106:107]
	v_cvt_pk_bf16_f32 v188, v108, v109
	v_lshl_add_u64 v[108:109], s[28:29], 0, v[112:113]
	v_pk_mul_f32 v[100:101], v[100:101], v[114:115] op_sel_hi:[1,0]
	v_pk_mul_f32 v[96:97], v[96:97], v[114:115] op_sel_hi:[1,0]
	v_cvt_pk_bf16_f32 v189, v110, v111
	v_cvt_pk_bf16_f32 v190, v116, v117
	v_cvt_pk_bf16_f32 v191, v118, v119
	v_lshl_add_u64 v[108:109], v[108:109], 0, v[120:121]
	v_pk_mul_f32 v[102:103], v[102:103], v[114:115] op_sel_hi:[1,0]
	v_max_f32_e32 v100, 0, v100
	v_max_f32_e32 v96, 0, v96
	v_max_f32_e32 v101, 0, v101
	v_max_f32_e32 v97, 0, v97
	v_pk_mul_f32 v[100:101], v[100:101], v[100:101]
	v_pk_mul_f32 v[98:99], v[98:99], v[114:115] op_sel_hi:[1,0]
	v_pk_mul_f32 v[104:105], v[96:97], v[96:97]
	v_max_f32_e32 v96, 0, v102
	v_max_f32_e32 v97, 0, v103
	v_pk_mul_f32 v[102:103], v[96:97], v[96:97]
	v_cvt_pk_bf16_f32 v96, v100, v101
	ds_read2_b32 v[100:101], v172 offset0:32 offset1:48
	v_max_f32_e32 v98, 0, v98
	v_max_f32_e32 v99, 0, v99
	v_pk_mul_f32 v[106:107], v[98:99], v[98:99]
	v_cvt_pk_bf16_f32 v97, v102, v103
	v_cvt_pk_bf16_f32 v98, v104, v105
	v_cvt_pk_bf16_f32 v99, v106, v107
	s_nop 1
	v_cndmask_b32_dpp v204, v96, v188, vcc quad_perm:[0,0,2,2] row_mask:0xf bank_mask:0xf
	v_cndmask_b32_dpp v205, v97, v189, vcc quad_perm:[0,0,2,2] row_mask:0xf bank_mask:0xf
	v_cndmask_b32_dpp v206, v98, v190, vcc quad_perm:[0,0,2,2] row_mask:0xf bank_mask:0xf
	v_cndmask_b32_dpp v207, v99, v191, vcc quad_perm:[0,0,2,2] row_mask:0xf bank_mask:0xf
	s_not_b64 vcc, vcc
	v_cndmask_b32_dpp v96, v188, v96, vcc quad_perm:[1,1,3,3] row_mask:0xf bank_mask:0xf
	v_cndmask_b32_dpp v97, v189, v97, vcc quad_perm:[1,1,3,3] row_mask:0xf bank_mask:0xf
	v_cndmask_b32_dpp v98, v190, v98, vcc quad_perm:[1,1,3,3] row_mask:0xf bank_mask:0xf
	v_cndmask_b32_dpp v99, v191, v99, vcc quad_perm:[1,1,3,3] row_mask:0xf bank_mask:0xf
	s_not_b64 vcc, vcc
	v_lshl_add_u64 v[218:219], v[108:109], 0, s[100:101]
	global_store_dwordx4 v[108:109], v[204:207], off nt
	global_store_dwordx4 v[218:219], v[96:99], off nt
	s_nop 1
	s_waitcnt lgkmcnt(0)
	v_pk_mul_f32 v[92:93], v[92:93], v[100:101] op_sel_hi:[1,0]
	v_pk_mul_f32 v[88:89], v[88:89], v[100:101] op_sel_hi:[1,0]
	v_add_u32_e32 v96, s17, v147
	v_ashrrev_i32_e32 v97, 31, v96
	v_pk_mul_f32 v[94:95], v[94:95], v[100:101] op_sel_hi:[1,0]
	v_pk_mul_f32 v[90:91], v[90:91], v[100:101] op_sel_hi:[1,0]
	v_max_f32_e32 v92, 0, v92
	v_max_f32_e32 v88, 0, v88
	v_max_f32_e32 v93, 0, v93
	v_max_f32_e32 v89, 0, v89
	v_lshlrev_b64 v[96:97], 14, v[96:97]
	v_pk_mul_f32 v[92:93], v[92:93], v[92:93]
	v_pk_mul_f32 v[98:99], v[88:89], v[88:89]
	v_max_f32_e32 v88, 0, v94
	v_max_f32_e32 v90, 0, v90
	v_max_f32_e32 v89, 0, v95
	v_max_f32_e32 v91, 0, v91
	v_pk_mul_f32 v[94:95], v[88:89], v[88:89]
	v_pk_mul_f32 v[102:103], v[90:91], v[90:91]
	v_cvt_pk_bf16_f32 v192, v92, v93
	v_lshl_add_u64 v[92:93], s[28:29], 0, v[96:97]
	v_pk_mul_f32 v[80:81], v[80:81], v[100:101] op_sel_hi:[1,0]
	v_cvt_pk_bf16_f32 v193, v94, v95
	v_cvt_pk_bf16_f32 v194, v98, v99
	v_cvt_pk_bf16_f32 v195, v102, v103
	v_lshl_add_u64 v[92:93], v[92:93], 0, v[120:121]
	v_pk_mul_f32 v[86:87], v[86:87], v[100:101] op_sel_hi:[1,0]
	v_pk_mul_f32 v[84:85], v[84:85], v[100:101] op_sel_hi:[1,0]
	v_pk_mul_f32 v[82:83], v[82:83], v[100:101] op_sel_hi:[1,0]
	v_max_f32_e32 v80, 0, v80
	v_max_f32_e32 v81, 0, v81
	v_max_f32_e32 v84, 0, v84
	v_max_f32_e32 v85, 0, v85
	v_pk_mul_f32 v[88:89], v[80:81], v[80:81]
	v_max_f32_e32 v80, 0, v86
	v_max_f32_e32 v82, 0, v82
	v_max_f32_e32 v81, 0, v87
	v_max_f32_e32 v83, 0, v83
	v_pk_mul_f32 v[84:85], v[84:85], v[84:85]
	v_pk_mul_f32 v[86:87], v[80:81], v[80:81]
	v_pk_mul_f32 v[90:91], v[82:83], v[82:83]
	v_cvt_pk_bf16_f32 v80, v84, v85
	v_cvt_pk_bf16_f32 v81, v86, v87
	v_cvt_pk_bf16_f32 v82, v88, v89
	v_cvt_pk_bf16_f32 v83, v90, v91
	s_nop 1
	v_cndmask_b32_dpp v208, v80, v192, vcc quad_perm:[0,0,2,2] row_mask:0xf bank_mask:0xf
	v_cndmask_b32_dpp v209, v81, v193, vcc quad_perm:[0,0,2,2] row_mask:0xf bank_mask:0xf
	v_cndmask_b32_dpp v210, v82, v194, vcc quad_perm:[0,0,2,2] row_mask:0xf bank_mask:0xf
	v_cndmask_b32_dpp v211, v83, v195, vcc quad_perm:[0,0,2,2] row_mask:0xf bank_mask:0xf
	s_not_b64 vcc, vcc
	v_cndmask_b32_dpp v80, v192, v80, vcc quad_perm:[1,1,3,3] row_mask:0xf bank_mask:0xf
	v_cndmask_b32_dpp v81, v193, v81, vcc quad_perm:[1,1,3,3] row_mask:0xf bank_mask:0xf
	v_cndmask_b32_dpp v82, v194, v82, vcc quad_perm:[1,1,3,3] row_mask:0xf bank_mask:0xf
	v_cndmask_b32_dpp v83, v195, v83, vcc quad_perm:[1,1,3,3] row_mask:0xf bank_mask:0xf
	s_not_b64 vcc, vcc
	v_lshl_add_u64 v[216:217], v[92:93], 0, s[100:101]
	global_store_dwordx4 v[92:93], v[208:211], off nt
	global_store_dwordx4 v[216:217], v[80:83], off nt
	s_nop 1
	s_nop 1
	v_mov_b32_e32 v82, v101
	v_add_u32_e32 v80, s17, v148
	v_pk_mul_f32 v[76:77], v[76:77], v[82:83] op_sel_hi:[1,0]
	v_pk_mul_f32 v[72:73], v[72:73], v[82:83] op_sel_hi:[1,0]
	v_ashrrev_i32_e32 v81, 31, v80
	v_pk_mul_f32 v[78:79], v[78:79], v[82:83] op_sel_hi:[1,0]
	v_pk_mul_f32 v[74:75], v[74:75], v[82:83] op_sel_hi:[1,0]
	v_max_f32_e32 v76, 0, v76
	v_max_f32_e32 v72, 0, v72
	v_max_f32_e32 v77, 0, v77
	v_max_f32_e32 v73, 0, v73
	v_lshlrev_b64 v[80:81], 14, v[80:81]
	v_pk_mul_f32 v[76:77], v[76:77], v[76:77]
	v_pk_mul_f32 v[84:85], v[72:73], v[72:73]
	v_max_f32_e32 v72, 0, v78
	v_max_f32_e32 v74, 0, v74
	v_max_f32_e32 v73, 0, v79
	v_max_f32_e32 v75, 0, v75
	v_pk_mul_f32 v[78:79], v[72:73], v[72:73]
	v_pk_mul_f32 v[86:87], v[74:75], v[74:75]
	v_cvt_pk_bf16_f32 v196, v76, v77
	v_lshl_add_u64 v[76:77], s[28:29], 0, v[80:81]
	v_pk_mul_f32 v[68:69], v[68:69], v[82:83] op_sel_hi:[1,0]
	v_pk_mul_f32 v[64:65], v[64:65], v[82:83] op_sel_hi:[1,0]
	v_cvt_pk_bf16_f32 v197, v78, v79
	v_cvt_pk_bf16_f32 v198, v84, v85
	v_cvt_pk_bf16_f32 v199, v86, v87
	v_lshl_add_u64 v[76:77], v[76:77], 0, v[120:121]
	v_pk_mul_f32 v[70:71], v[70:71], v[82:83] op_sel_hi:[1,0]
	v_max_f32_e32 v68, 0, v68
	v_max_f32_e32 v64, 0, v64
	v_max_f32_e32 v69, 0, v69
	v_max_f32_e32 v65, 0, v65
	v_pk_mul_f32 v[68:69], v[68:69], v[68:69]
	v_pk_mul_f32 v[66:67], v[66:67], v[82:83] op_sel_hi:[1,0]
	v_pk_mul_f32 v[72:73], v[64:65], v[64:65]
	v_max_f32_e32 v64, 0, v70
	v_max_f32_e32 v65, 0, v71
	v_pk_mul_f32 v[70:71], v[64:65], v[64:65]
	v_cvt_pk_bf16_f32 v64, v68, v69
	ds_read2_b32 v[68:69], v172 offset0:128 offset1:144
	v_max_f32_e32 v66, 0, v66
	v_max_f32_e32 v67, 0, v67
	v_pk_mul_f32 v[74:75], v[66:67], v[66:67]
	v_cvt_pk_bf16_f32 v65, v70, v71
	v_cvt_pk_bf16_f32 v66, v72, v73
	v_cvt_pk_bf16_f32 v67, v74, v75
	s_nop 1
	v_cndmask_b32_dpp v212, v64, v196, vcc quad_perm:[0,0,2,2] row_mask:0xf bank_mask:0xf
	v_cndmask_b32_dpp v213, v65, v197, vcc quad_perm:[0,0,2,2] row_mask:0xf bank_mask:0xf
	v_cndmask_b32_dpp v214, v66, v198, vcc quad_perm:[0,0,2,2] row_mask:0xf bank_mask:0xf
	v_cndmask_b32_dpp v215, v67, v199, vcc quad_perm:[0,0,2,2] row_mask:0xf bank_mask:0xf
	s_not_b64 vcc, vcc
	v_cndmask_b32_dpp v64, v196, v64, vcc quad_perm:[1,1,3,3] row_mask:0xf bank_mask:0xf
	v_cndmask_b32_dpp v65, v197, v65, vcc quad_perm:[1,1,3,3] row_mask:0xf bank_mask:0xf
	v_cndmask_b32_dpp v66, v198, v66, vcc quad_perm:[1,1,3,3] row_mask:0xf bank_mask:0xf
	v_cndmask_b32_dpp v67, v199, v67, vcc quad_perm:[1,1,3,3] row_mask:0xf bank_mask:0xf
	s_not_b64 vcc, vcc
	v_lshl_add_u64 v[218:219], v[76:77], 0, s[100:101]
	global_store_dwordx4 v[76:77], v[212:215], off nt
	global_store_dwordx4 v[218:219], v[64:67], off nt
	s_nop 1
	s_waitcnt lgkmcnt(0)
	v_pk_mul_f32 v[60:61], v[60:61], v[68:69] op_sel_hi:[1,0]
	v_pk_mul_f32 v[56:57], v[56:57], v[68:69] op_sel_hi:[1,0]
	v_add_u32_e32 v64, s17, v149
	v_ashrrev_i32_e32 v65, 31, v64
	v_pk_mul_f32 v[62:63], v[62:63], v[68:69] op_sel_hi:[1,0]
	v_pk_mul_f32 v[58:59], v[58:59], v[68:69] op_sel_hi:[1,0]
	v_max_f32_e32 v60, 0, v60
	v_max_f32_e32 v56, 0, v56
	v_max_f32_e32 v61, 0, v61
	v_max_f32_e32 v57, 0, v57
	v_lshlrev_b64 v[64:65], 14, v[64:65]
	v_pk_mul_f32 v[60:61], v[60:61], v[60:61]
	v_pk_mul_f32 v[66:67], v[56:57], v[56:57]
	v_max_f32_e32 v56, 0, v62
	v_max_f32_e32 v58, 0, v58
	v_max_f32_e32 v57, 0, v63
	v_max_f32_e32 v59, 0, v59
	v_pk_mul_f32 v[62:63], v[56:57], v[56:57]
	v_pk_mul_f32 v[70:71], v[58:59], v[58:59]
	v_cvt_pk_bf16_f32 v184, v60, v61
	v_lshl_add_u64 v[60:61], s[28:29], 0, v[64:65]
	v_pk_mul_f32 v[48:49], v[48:49], v[68:69] op_sel_hi:[1,0]
	v_cvt_pk_bf16_f32 v185, v62, v63
	v_cvt_pk_bf16_f32 v186, v66, v67
	v_cvt_pk_bf16_f32 v187, v70, v71
	v_lshl_add_u64 v[60:61], v[60:61], 0, v[120:121]
	v_pk_mul_f32 v[54:55], v[54:55], v[68:69] op_sel_hi:[1,0]
	v_pk_mul_f32 v[52:53], v[52:53], v[68:69] op_sel_hi:[1,0]
	v_pk_mul_f32 v[50:51], v[50:51], v[68:69] op_sel_hi:[1,0]
	v_max_f32_e32 v48, 0, v48
	v_max_f32_e32 v49, 0, v49
	v_max_f32_e32 v52, 0, v52
	v_max_f32_e32 v53, 0, v53
	v_pk_mul_f32 v[56:57], v[48:49], v[48:49]
	v_max_f32_e32 v48, 0, v54
	v_max_f32_e32 v50, 0, v50
	v_max_f32_e32 v49, 0, v55
	v_max_f32_e32 v51, 0, v51
	v_pk_mul_f32 v[52:53], v[52:53], v[52:53]
	v_pk_mul_f32 v[54:55], v[48:49], v[48:49]
	v_pk_mul_f32 v[58:59], v[50:51], v[50:51]
	v_cvt_pk_bf16_f32 v48, v52, v53
	v_cvt_pk_bf16_f32 v49, v54, v55
	v_cvt_pk_bf16_f32 v50, v56, v57
	v_cvt_pk_bf16_f32 v51, v58, v59
	s_nop 1
	v_cndmask_b32_dpp v200, v48, v184, vcc quad_perm:[0,0,2,2] row_mask:0xf bank_mask:0xf
	v_cndmask_b32_dpp v201, v49, v185, vcc quad_perm:[0,0,2,2] row_mask:0xf bank_mask:0xf
	v_cndmask_b32_dpp v202, v50, v186, vcc quad_perm:[0,0,2,2] row_mask:0xf bank_mask:0xf
	v_cndmask_b32_dpp v203, v51, v187, vcc quad_perm:[0,0,2,2] row_mask:0xf bank_mask:0xf
	s_not_b64 vcc, vcc
	v_cndmask_b32_dpp v48, v184, v48, vcc quad_perm:[1,1,3,3] row_mask:0xf bank_mask:0xf
	v_cndmask_b32_dpp v49, v185, v49, vcc quad_perm:[1,1,3,3] row_mask:0xf bank_mask:0xf
	v_cndmask_b32_dpp v50, v186, v50, vcc quad_perm:[1,1,3,3] row_mask:0xf bank_mask:0xf
	v_cndmask_b32_dpp v51, v187, v51, vcc quad_perm:[1,1,3,3] row_mask:0xf bank_mask:0xf
	s_not_b64 vcc, vcc
	v_lshl_add_u64 v[216:217], v[60:61], 0, s[100:101]
	global_store_dwordx4 v[60:61], v[200:203], off nt
	global_store_dwordx4 v[216:217], v[48:51], off nt
	s_nop 1
	s_nop 1
	v_mov_b32_e32 v50, v69
	v_add_u32_e32 v48, s17, v150
	v_pk_mul_f32 v[44:45], v[44:45], v[50:51] op_sel_hi:[1,0]
	v_pk_mul_f32 v[40:41], v[40:41], v[50:51] op_sel_hi:[1,0]
	v_ashrrev_i32_e32 v49, 31, v48
	v_pk_mul_f32 v[46:47], v[46:47], v[50:51] op_sel_hi:[1,0]
	v_pk_mul_f32 v[42:43], v[42:43], v[50:51] op_sel_hi:[1,0]
	v_max_f32_e32 v44, 0, v44
	v_max_f32_e32 v40, 0, v40
	v_max_f32_e32 v45, 0, v45
	v_max_f32_e32 v41, 0, v41
	v_lshlrev_b64 v[48:49], 14, v[48:49]
	v_pk_mul_f32 v[44:45], v[44:45], v[44:45]
	v_pk_mul_f32 v[52:53], v[40:41], v[40:41]
	v_max_f32_e32 v40, 0, v46
	v_max_f32_e32 v42, 0, v42
	v_max_f32_e32 v41, 0, v47
	v_max_f32_e32 v43, 0, v43
	v_pk_mul_f32 v[46:47], v[40:41], v[40:41]
	v_pk_mul_f32 v[54:55], v[42:43], v[42:43]
	v_cvt_pk_bf16_f32 v188, v44, v45
	v_lshl_add_u64 v[44:45], s[28:29], 0, v[48:49]
	v_pk_mul_f32 v[36:37], v[36:37], v[50:51] op_sel_hi:[1,0]
	v_pk_mul_f32 v[32:33], v[32:33], v[50:51] op_sel_hi:[1,0]
	v_cvt_pk_bf16_f32 v189, v46, v47
	v_cvt_pk_bf16_f32 v190, v52, v53
	v_cvt_pk_bf16_f32 v191, v54, v55
	v_lshl_add_u64 v[44:45], v[44:45], 0, v[120:121]
	v_pk_mul_f32 v[38:39], v[38:39], v[50:51] op_sel_hi:[1,0]
	v_max_f32_e32 v36, 0, v36
	v_max_f32_e32 v32, 0, v32
	v_max_f32_e32 v37, 0, v37
	v_max_f32_e32 v33, 0, v33
	v_pk_mul_f32 v[36:37], v[36:37], v[36:37]
	v_pk_mul_f32 v[34:35], v[34:35], v[50:51] op_sel_hi:[1,0]
	v_pk_mul_f32 v[40:41], v[32:33], v[32:33]
	v_max_f32_e32 v32, 0, v38
	v_max_f32_e32 v33, 0, v39
	v_pk_mul_f32 v[38:39], v[32:33], v[32:33]
	v_cvt_pk_bf16_f32 v32, v36, v37
	ds_read2_b32 v[36:37], v172 offset0:160 offset1:176
	v_max_f32_e32 v34, 0, v34
	v_max_f32_e32 v35, 0, v35
	v_pk_mul_f32 v[42:43], v[34:35], v[34:35]
	v_cvt_pk_bf16_f32 v33, v38, v39
	v_cvt_pk_bf16_f32 v34, v40, v41
	v_cvt_pk_bf16_f32 v35, v42, v43
	s_nop 1
	v_cndmask_b32_dpp v204, v32, v188, vcc quad_perm:[0,0,2,2] row_mask:0xf bank_mask:0xf
	v_cndmask_b32_dpp v205, v33, v189, vcc quad_perm:[0,0,2,2] row_mask:0xf bank_mask:0xf
	v_cndmask_b32_dpp v206, v34, v190, vcc quad_perm:[0,0,2,2] row_mask:0xf bank_mask:0xf
	v_cndmask_b32_dpp v207, v35, v191, vcc quad_perm:[0,0,2,2] row_mask:0xf bank_mask:0xf
	s_not_b64 vcc, vcc
	v_cndmask_b32_dpp v32, v188, v32, vcc quad_perm:[1,1,3,3] row_mask:0xf bank_mask:0xf
	v_cndmask_b32_dpp v33, v189, v33, vcc quad_perm:[1,1,3,3] row_mask:0xf bank_mask:0xf
	v_cndmask_b32_dpp v34, v190, v34, vcc quad_perm:[1,1,3,3] row_mask:0xf bank_mask:0xf
	v_cndmask_b32_dpp v35, v191, v35, vcc quad_perm:[1,1,3,3] row_mask:0xf bank_mask:0xf
	s_not_b64 vcc, vcc
	v_lshl_add_u64 v[218:219], v[44:45], 0, s[100:101]
	global_store_dwordx4 v[44:45], v[204:207], off nt
	global_store_dwordx4 v[218:219], v[32:35], off nt
	s_nop 1
	s_waitcnt lgkmcnt(0)
	v_pk_mul_f32 v[28:29], v[28:29], v[36:37] op_sel_hi:[1,0]
	v_pk_mul_f32 v[24:25], v[24:25], v[36:37] op_sel_hi:[1,0]
	v_add_u32_e32 v32, s17, v151
	v_ashrrev_i32_e32 v33, 31, v32
	v_pk_mul_f32 v[30:31], v[30:31], v[36:37] op_sel_hi:[1,0]
	v_pk_mul_f32 v[26:27], v[26:27], v[36:37] op_sel_hi:[1,0]
	v_max_f32_e32 v28, 0, v28
	v_max_f32_e32 v24, 0, v24
	v_max_f32_e32 v29, 0, v29
	v_max_f32_e32 v25, 0, v25
	v_lshlrev_b64 v[32:33], 14, v[32:33]
	v_pk_mul_f32 v[28:29], v[28:29], v[28:29]
	v_pk_mul_f32 v[34:35], v[24:25], v[24:25]
	v_max_f32_e32 v24, 0, v30
	v_max_f32_e32 v26, 0, v26
	v_max_f32_e32 v25, 0, v31
	v_max_f32_e32 v27, 0, v27
	v_pk_mul_f32 v[30:31], v[24:25], v[24:25]
	v_pk_mul_f32 v[38:39], v[26:27], v[26:27]
	v_cvt_pk_bf16_f32 v192, v28, v29
	v_lshl_add_u64 v[28:29], s[28:29], 0, v[32:33]
	v_pk_mul_f32 v[16:17], v[16:17], v[36:37] op_sel_hi:[1,0]
	v_cvt_pk_bf16_f32 v193, v30, v31
	v_cvt_pk_bf16_f32 v194, v34, v35
	v_cvt_pk_bf16_f32 v195, v38, v39
	v_lshl_add_u64 v[28:29], v[28:29], 0, v[120:121]
	v_pk_mul_f32 v[22:23], v[22:23], v[36:37] op_sel_hi:[1,0]
	v_pk_mul_f32 v[20:21], v[20:21], v[36:37] op_sel_hi:[1,0]
	v_pk_mul_f32 v[18:19], v[18:19], v[36:37] op_sel_hi:[1,0]
	v_max_f32_e32 v16, 0, v16
	v_max_f32_e32 v17, 0, v17
	v_max_f32_e32 v20, 0, v20
	v_max_f32_e32 v21, 0, v21
	v_pk_mul_f32 v[24:25], v[16:17], v[16:17]
	v_max_f32_e32 v16, 0, v22
	v_max_f32_e32 v18, 0, v18
	v_max_f32_e32 v17, 0, v23
	v_max_f32_e32 v19, 0, v19
	v_pk_mul_f32 v[20:21], v[20:21], v[20:21]
	v_pk_mul_f32 v[22:23], v[16:17], v[16:17]
	v_pk_mul_f32 v[26:27], v[18:19], v[18:19]
	v_cvt_pk_bf16_f32 v16, v20, v21
	v_cvt_pk_bf16_f32 v17, v22, v23
	v_cvt_pk_bf16_f32 v18, v24, v25
	v_cvt_pk_bf16_f32 v19, v26, v27
	s_nop 1
	v_cndmask_b32_dpp v208, v16, v192, vcc quad_perm:[0,0,2,2] row_mask:0xf bank_mask:0xf
	v_cndmask_b32_dpp v209, v17, v193, vcc quad_perm:[0,0,2,2] row_mask:0xf bank_mask:0xf
	v_cndmask_b32_dpp v210, v18, v194, vcc quad_perm:[0,0,2,2] row_mask:0xf bank_mask:0xf
	v_cndmask_b32_dpp v211, v19, v195, vcc quad_perm:[0,0,2,2] row_mask:0xf bank_mask:0xf
	s_not_b64 vcc, vcc
	v_cndmask_b32_dpp v16, v192, v16, vcc quad_perm:[1,1,3,3] row_mask:0xf bank_mask:0xf
	v_cndmask_b32_dpp v17, v193, v17, vcc quad_perm:[1,1,3,3] row_mask:0xf bank_mask:0xf
	v_cndmask_b32_dpp v18, v194, v18, vcc quad_perm:[1,1,3,3] row_mask:0xf bank_mask:0xf
	v_cndmask_b32_dpp v19, v195, v19, vcc quad_perm:[1,1,3,3] row_mask:0xf bank_mask:0xf
	s_not_b64 vcc, vcc
	v_lshl_add_u64 v[216:217], v[28:29], 0, s[100:101]
	global_store_dwordx4 v[28:29], v[208:211], off nt
	global_store_dwordx4 v[216:217], v[16:19], off nt
	s_nop 1
	s_nop 1
	v_mov_b32_e32 v18, v37
	v_add_u32_e32 v16, s17, v152
	v_pk_mul_f32 v[12:13], v[12:13], v[18:19] op_sel_hi:[1,0]
	v_pk_mul_f32 v[8:9], v[8:9], v[18:19] op_sel_hi:[1,0]
	v_ashrrev_i32_e32 v17, 31, v16
	v_pk_mul_f32 v[14:15], v[14:15], v[18:19] op_sel_hi:[1,0]
	v_pk_mul_f32 v[10:11], v[10:11], v[18:19] op_sel_hi:[1,0]
	v_max_f32_e32 v12, 0, v12
	v_max_f32_e32 v8, 0, v8
	v_max_f32_e32 v13, 0, v13
	v_max_f32_e32 v9, 0, v9
	v_lshlrev_b64 v[16:17], 14, v[16:17]
	v_pk_mul_f32 v[12:13], v[12:13], v[12:13]
	v_pk_mul_f32 v[20:21], v[8:9], v[8:9]
	v_max_f32_e32 v8, 0, v14
	v_max_f32_e32 v10, 0, v10
	v_max_f32_e32 v9, 0, v15
	v_max_f32_e32 v11, 0, v11
	v_pk_mul_f32 v[14:15], v[8:9], v[8:9]
	v_pk_mul_f32 v[22:23], v[10:11], v[10:11]
	v_cvt_pk_bf16_f32 v196, v12, v13
	v_lshl_add_u64 v[12:13], s[28:29], 0, v[16:17]
	v_pk_mul_f32 v[0:1], v[0:1], v[18:19] op_sel_hi:[1,0]
	v_cvt_pk_bf16_f32 v197, v14, v15
	v_cvt_pk_bf16_f32 v198, v20, v21
	v_cvt_pk_bf16_f32 v199, v22, v23
	v_lshl_add_u64 v[12:13], v[12:13], 0, v[120:121]
	v_pk_mul_f32 v[6:7], v[6:7], v[18:19] op_sel_hi:[1,0]
	v_pk_mul_f32 v[4:5], v[4:5], v[18:19] op_sel_hi:[1,0]
	v_pk_mul_f32 v[2:3], v[2:3], v[18:19] op_sel_hi:[1,0]
	v_max_f32_e32 v0, 0, v0
	v_max_f32_e32 v1, 0, v1
	v_max_f32_e32 v4, 0, v4
	v_max_f32_e32 v5, 0, v5
	v_pk_mul_f32 v[8:9], v[0:1], v[0:1]
	v_max_f32_e32 v0, 0, v6
	v_max_f32_e32 v2, 0, v2
	v_max_f32_e32 v1, 0, v7
	v_max_f32_e32 v3, 0, v3
	v_pk_mul_f32 v[4:5], v[4:5], v[4:5]
	v_pk_mul_f32 v[6:7], v[0:1], v[0:1]
	v_pk_mul_f32 v[10:11], v[2:3], v[2:3]
	v_cvt_pk_bf16_f32 v0, v4, v5
	v_cvt_pk_bf16_f32 v1, v6, v7
	v_cvt_pk_bf16_f32 v2, v8, v9
	v_cvt_pk_bf16_f32 v3, v10, v11
	s_nop 1
	v_cndmask_b32_dpp v212, v0, v196, vcc quad_perm:[0,0,2,2] row_mask:0xf bank_mask:0xf
	v_cndmask_b32_dpp v213, v1, v197, vcc quad_perm:[0,0,2,2] row_mask:0xf bank_mask:0xf
	v_cndmask_b32_dpp v214, v2, v198, vcc quad_perm:[0,0,2,2] row_mask:0xf bank_mask:0xf
	v_cndmask_b32_dpp v215, v3, v199, vcc quad_perm:[0,0,2,2] row_mask:0xf bank_mask:0xf
	s_not_b64 vcc, vcc
	v_cndmask_b32_dpp v0, v196, v0, vcc quad_perm:[1,1,3,3] row_mask:0xf bank_mask:0xf
	v_cndmask_b32_dpp v1, v197, v1, vcc quad_perm:[1,1,3,3] row_mask:0xf bank_mask:0xf
	v_cndmask_b32_dpp v2, v198, v2, vcc quad_perm:[1,1,3,3] row_mask:0xf bank_mask:0xf
	v_cndmask_b32_dpp v3, v199, v3, vcc quad_perm:[1,1,3,3] row_mask:0xf bank_mask:0xf
	s_not_b64 vcc, vcc
	v_lshl_add_u64 v[218:219], v[12:13], 0, s[100:101]
	global_store_dwordx4 v[12:13], v[212:215], off nt
	global_store_dwordx4 v[218:219], v[0:3], off nt
	s_nop 1
	s_andn2_b64 vcc, exec, s[6:7]
	s_mov_b64 s[6:7], -1
	s_cbranch_vccnz .LBB0_439
	s_andn2_b64 vcc, exec, s[10:11]
	s_cbranch_vccnz .LBB0_438
	s_barrier
	s_branch .LBB0_438
